# layer-0 modulate row loop rewritten: scalar row control, next row pair prefetched, adaLN vectors batched, pointers in SGPRs
# speedup vs baseline: 1.2243x; 1.0081x over previous
; __device__ __forceinline__ int tid_() { int t = threadIdx.x; asm volatile("" : "+v"(t)); return t; }
; __device__ __forceinline__ int bid_() { int b = blockIdx.x; asm volatile("" : "+s"(b)); return b; }
; template <bool COMBINE, bool MOD>
; __device__ __forceinline__ void phase_combine_modulate(const Params& p, int lprev, int lnext, const float* xlat, const float* xctx,
;                                                        float* olat, float* octx, int nrows) {
;     ...
;   const int t = tid_(), lane = t & 63, wid = t >> 6;
;   const int gw = bid_() * 4 + wid, nw = gridDim.x * 4;
;   for (int row0 = gw * R; row0 < nrows; row0 += nw * R) {
;     const bool lat = row0 < T_LAT;
;     const float* xr = lat ? xlat + (size_t)row0 * DM : xctx + (size_t)(row0 - T_LAT) * DM;
;     const int cond = row_cond(row0);
;     float4 v[R][4];
; #pragma unroll
;     for (int r = 0; r < R; ++r)
; #pragma unroll
;       for (int i = 0; i < 4; ++i) v[r][i] = *(const float4*)(xr + (size_t)r * DM + i * 256 + lane * 4);
;     ...
;     if (MOD) {
;       const float* sh = p.mada + (size_t)(lnext * 3 + cond) * 6144;
;       const float* sc = sh + 1024;
;       float rstd[R];
; #pragma unroll
;       for (int r = 0; r < R; ++r) {
;         float ss = 0.f;
; #pragma unroll
;         for (int i = 0; i < 4; ++i) ss += v[r][i].x * v[r][i].x + v[r][i].y * v[r][i].y + v[r][i].z * v[r][i].z + v[r][i].w * v[r][i].w;
;         rstd[r] = rsqrtf(wave_sum(ss) * (1.f / 1024.f) + 1e-6f);
;       }
.LBB0_150:
	s_or_b64 exec, exec, s[40:41]
	s_mov_b64 s[0:1], s[64:65]
	v_mov_b32_e32 v0, v187
	s_mov_b32 s8, s2
	v_ashrrev_i32_e32 v2, 5, v0
	v_and_b32_e32 v2, -2, v2
	s_nop 0
	v_lshl_add_u32 v38, s8, 3, v2
	v_cmp_gt_i32_e32 vcc, s68, v38
	s_and_saveexec_b64 s[40:41], vcc
	s_cbranch_execz .LBB0_155
	s_load_dwordx2 s[8:9], s[64:65], 0x0
	s_load_dwordx2 s[34:35], s[64:65], 0x10
	s_load_dwordx2 s[48:49], s[64:65], 0xb8
	s_load_dwordx2 s[50:51], s[64:65], 0x118
	v_readfirstlane_b32 s38, v38
	v_readlane_b32 s39, v254, 54
	s_mov_b32 s101, 0x3a800000
	v_and_b32_e32 v0, 63, v187
	v_lshlrev_b32_e32 v80, 4, v0
	v_or_b32_e32 v81, 0x1000, v80
	v_lshlrev_b32_e32 v82, 3, v0
	v_xor_b32_e32 v83, 16, v0
	v_xor_b32_e32 v84, 32, v0
	v_lshlrev_b32_e32 v83, 2, v83
	v_lshlrev_b32_e32 v84, 2, v84
	s_waitcnt lgkmcnt(0)
	s_cmpk_lt_i32 s38, 0x4000
	s_cselect_b32 s0, s8, s34
	s_cselect_b32 s1, s9, s35
	s_cselect_b32 s56, 0, 0x4000
	s_sub_i32 s56, s38, s56
	s_lshl_b32 s56, s56, 12
	s_add_u32 s52, s0, s56
	s_addc_u32 s53, s1, 0
	global_load_dwordx4 v[100:103], v80, s[52:53]
	global_load_dwordx4 v[104:107], v80, s[52:53] offset:1024
	global_load_dwordx4 v[108:111], v80, s[52:53] offset:2048
	global_load_dwordx4 v[112:115], v80, s[52:53] offset:3072
	global_load_dwordx4 v[116:119], v81, s[52:53]
	global_load_dwordx4 v[120:123], v81, s[52:53] offset:1024
	global_load_dwordx4 v[124:127], v81, s[52:53] offset:2048
	global_load_dwordx4 v[128:131], v81, s[52:53] offset:3072
.Lmd0_loop:
	s_add_i32 s100, s38, s39
	s_cmp_lt_i32 s100, s68
	s_cbranch_scc0 .Lmd0_last_a
	s_min_i32 s0, s38, 0x4000
	s_ashr_i32 s0, s0, 13
	s_mul_i32 s0, s0, 0x6000
	s_add_u32 s56, s48, s0
	s_addc_u32 s57, s49, 0
	s_lshl_b32 s0, s38, 11
	s_add_u32 s98, s50, s0
	s_addc_u32 s99, s51, 0
	global_load_dwordx4 v[20:23], v80, s[56:57]
	global_load_dwordx4 v[24:27], v80, s[56:57] offset:1024
	global_load_dwordx4 v[28:31], v80, s[56:57] offset:2048
	global_load_dwordx4 v[32:35], v80, s[56:57] offset:3072
	global_load_dwordx4 v[36:39], v81, s[56:57]
	global_load_dwordx4 v[40:43], v81, s[56:57] offset:1024
	global_load_dwordx4 v[44:47], v81, s[56:57] offset:2048
	global_load_dwordx4 v[48:51], v81, s[56:57] offset:3072
	s_cmpk_lt_i32 s100, 0x4000
	s_cselect_b32 s0, s8, s34
	s_cselect_b32 s1, s9, s35
	s_cselect_b32 s56, 0, 0x4000
	s_sub_i32 s56, s100, s56
	s_lshl_b32 s56, s56, 12
	s_add_u32 s52, s0, s56
	s_addc_u32 s53, s1, 0
	global_load_dwordx4 v[132:135], v80, s[52:53]
	global_load_dwordx4 v[136:139], v80, s[52:53] offset:1024
	global_load_dwordx4 v[140:143], v80, s[52:53] offset:2048
	global_load_dwordx4 v[144:147], v80, s[52:53] offset:3072
	global_load_dwordx4 v[148:151], v81, s[52:53]
	global_load_dwordx4 v[152:155], v81, s[52:53] offset:1024
	global_load_dwordx4 v[156:159], v81, s[52:53] offset:2048
	global_load_dwordx4 v[160:163], v81, s[52:53] offset:3072
	s_waitcnt vmcnt(16)
	v_pk_mul_f32 v[8:9], v[100:101], v[100:101]
	v_pk_fma_f32 v[8:9], v[102:103], v[102:103], v[8:9]
	v_pk_fma_f32 v[8:9], v[104:105], v[104:105], v[8:9]
	v_pk_fma_f32 v[8:9], v[106:107], v[106:107], v[8:9]
	v_pk_fma_f32 v[8:9], v[108:109], v[108:109], v[8:9]
	v_pk_fma_f32 v[8:9], v[110:111], v[110:111], v[8:9]
	v_pk_fma_f32 v[8:9], v[112:113], v[112:113], v[8:9]
	v_pk_fma_f32 v[8:9], v[114:115], v[114:115], v[8:9]
	v_pk_mul_f32 v[10:11], v[116:117], v[116:117]
	v_pk_fma_f32 v[10:11], v[118:119], v[118:119], v[10:11]
	v_pk_fma_f32 v[10:11], v[120:121], v[120:121], v[10:11]
	v_pk_fma_f32 v[10:11], v[122:123], v[122:123], v[10:11]
	v_pk_fma_f32 v[10:11], v[124:125], v[124:125], v[10:11]
	v_pk_fma_f32 v[10:11], v[126:127], v[126:127], v[10:11]
	v_pk_fma_f32 v[10:11], v[128:129], v[128:129], v[10:11]
	v_pk_fma_f32 v[10:11], v[130:131], v[130:131], v[10:11]
	v_add_f32_e32 v6, v8, v9
	v_add_f32_e32 v7, v10, v11
	s_nop 1
	v_add_f32_dpp v6, v6, v6 quad_perm:[1,0,3,2] row_mask:0xf bank_mask:0xf
	v_add_f32_dpp v7, v7, v7 quad_perm:[1,0,3,2] row_mask:0xf bank_mask:0xf
	s_nop 1
	v_add_f32_dpp v6, v6, v6 quad_perm:[2,3,0,1] row_mask:0xf bank_mask:0xf
	v_add_f32_dpp v7, v7, v7 quad_perm:[2,3,0,1] row_mask:0xf bank_mask:0xf
	s_nop 1
	v_add_f32_dpp v6, v6, v6 row_half_mirror row_mask:0xf bank_mask:0xf
	v_add_f32_dpp v7, v7, v7 row_half_mirror row_mask:0xf bank_mask:0xf
	s_nop 1
	v_add_f32_dpp v6, v6, v6 row_mirror row_mask:0xf bank_mask:0xf
	v_add_f32_dpp v7, v7, v7 row_mirror row_mask:0xf bank_mask:0xf
	ds_bpermute_b32 v8, v83, v6
	ds_bpermute_b32 v9, v83, v7
	s_waitcnt lgkmcnt(0)
	v_pk_add_f32 v[6:7], v[6:7], v[8:9]
	ds_bpermute_b32 v8, v84, v6
	ds_bpermute_b32 v9, v84, v7
	s_waitcnt lgkmcnt(0)
	v_pk_add_f32 v[6:7], v[6:7], v[8:9]
	s_nop 0
	v_fma_f32 v6, v6, s101, v224
	v_fma_f32 v7, v7, s101, v224
	v_mul_f32_e32 v2, 0x4b800000, v6
	v_cmp_gt_f32_e32 vcc, s85, v6
	v_cndmask_b32_e32 v2, v6, v2, vcc
	v_rsq_f32_e32 v2, v2
	s_nop 0
	v_mul_f32_e32 v6, 0x45800000, v2
	v_cndmask_b32_e32 v2, v2, v6, vcc
	v_mul_f32_e32 v4, 0x4b800000, v7
	v_cmp_gt_f32_e32 vcc, s85, v7
	v_cndmask_b32_e32 v4, v7, v4, vcc
	v_rsq_f32_e32 v4, v4
	s_nop 0
	v_mul_f32_e32 v7, 0x45800000, v4
	v_cndmask_b32_e32 v4, v4, v7, vcc
	s_waitcnt vmcnt(8)
; template <bool COMBINE, bool MOD>
; __device__ __forceinline__ void phase_combine_modulate(const Params& p, int lprev, int lnext, const float* xlat, const float* xctx,
;                                                        float* olat, float* octx, int nrows) {
;     ...
;   for (int row0 = gw * R; row0 < nrows; row0 += nw * R) {
;     const bool lat = row0 < T_LAT;
;     const float* xr = lat ? xlat + (size_t)row0 * DM : xctx + (size_t)(row0 - T_LAT) * DM;
;     const int cond = row_cond(row0);
;     float4 v[R][4];
; #pragma unroll
;     for (int r = 0; r < R; ++r)
; #pragma unroll
;       for (int i = 0; i < 4; ++i) v[r][i] = *(const float4*)(xr + (size_t)r * DM + i * 256 + lane * 4);
;     ...
;     if (MOD) {
;       const float* sh = p.mada + (size_t)(lnext * 3 + cond) * 6144;
;       const float* sc = sh + 1024;
;       float rstd[R];
; #pragma unroll
;       for (int r = 0; r < R; ++r) {
;         float ss = 0.f;
; #pragma unroll
;         for (int i = 0; i < 4; ++i) ss += v[r][i].x * v[r][i].x + v[r][i].y * v[r][i].y + v[r][i].z * v[r][i].z + v[r][i].w * v[r][i].w;
;         rstd[r] = rsqrtf(wave_sum(ss) * (1.f / 1024.f) + 1e-6f);
;       }
; #pragma unroll
;       for (int i = 0; i < 4; ++i) {
;         const int col = i * 256 + lane * 4;
;         const float4 s4 = *(const float4*)(sc + col);
;         const float4 h4 = *(const float4*)(sh + col);
; #pragma unroll
;         for (int r = 0; r < R; ++r) {
;           u32x2 pk;
;           pk.x = pack2(v[r][i].x * rstd[r] * (1.f + s4.x) + h4.x, v[r][i].y * rstd[r] * (1.f + s4.y) + h4.y);
;           pk.y = pack2(v[r][i].z * rstd[r] * (1.f + s4.z) + h4.z, v[r][i].w * rstd[r] * (1.f + s4.w) + h4.w);
;           *(u32x2*)(p.H + (size_t)(row0 + r) * DM + col) = pk;
;         }
;       }
	v_pk_add_f32 v[36:37], v[36:37], 1.0 op_sel_hi:[1,0]
	v_pk_add_f32 v[38:39], v[38:39], 1.0 op_sel_hi:[1,0]
	v_pk_mul_f32 v[8:9], v[100:101], v[2:3] op_sel_hi:[1,0]
	v_pk_mul_f32 v[10:11], v[102:103], v[2:3] op_sel_hi:[1,0]
	v_pk_fma_f32 v[8:9], v[36:37], v[8:9], v[20:21]
	v_pk_fma_f32 v[10:11], v[38:39], v[10:11], v[22:23]
	v_cvt_pk_bf16_f32 v52, v8, v9
	v_cvt_pk_bf16_f32 v53, v10, v11
	global_store_dwordx2 v82, v[52:53], s[98:99]
	v_pk_mul_f32 v[12:13], v[116:117], v[4:5] op_sel_hi:[1,0]
	v_pk_mul_f32 v[14:15], v[118:119], v[4:5] op_sel_hi:[1,0]
	v_pk_fma_f32 v[12:13], v[36:37], v[12:13], v[20:21]
	v_pk_fma_f32 v[14:15], v[38:39], v[14:15], v[22:23]
	v_cvt_pk_bf16_f32 v54, v12, v13
	v_cvt_pk_bf16_f32 v55, v14, v15
	global_store_dwordx2 v82, v[54:55], s[98:99] offset:2048
	v_pk_add_f32 v[40:41], v[40:41], 1.0 op_sel_hi:[1,0]
	v_pk_add_f32 v[42:43], v[42:43], 1.0 op_sel_hi:[1,0]
	v_pk_mul_f32 v[8:9], v[104:105], v[2:3] op_sel_hi:[1,0]
	v_pk_mul_f32 v[10:11], v[106:107], v[2:3] op_sel_hi:[1,0]
	v_pk_fma_f32 v[8:9], v[40:41], v[8:9], v[24:25]
	v_pk_fma_f32 v[10:11], v[42:43], v[10:11], v[26:27]
	v_cvt_pk_bf16_f32 v56, v8, v9
	v_cvt_pk_bf16_f32 v57, v10, v11
	global_store_dwordx2 v82, v[56:57], s[98:99] offset:512
	v_pk_mul_f32 v[12:13], v[120:121], v[4:5] op_sel_hi:[1,0]
	v_pk_mul_f32 v[14:15], v[122:123], v[4:5] op_sel_hi:[1,0]
	v_pk_fma_f32 v[12:13], v[40:41], v[12:13], v[24:25]
	v_pk_fma_f32 v[14:15], v[42:43], v[14:15], v[26:27]
	v_cvt_pk_bf16_f32 v58, v12, v13
	v_cvt_pk_bf16_f32 v59, v14, v15
	global_store_dwordx2 v82, v[58:59], s[98:99] offset:2560
	v_pk_add_f32 v[44:45], v[44:45], 1.0 op_sel_hi:[1,0]
	v_pk_add_f32 v[46:47], v[46:47], 1.0 op_sel_hi:[1,0]
	v_pk_mul_f32 v[8:9], v[108:109], v[2:3] op_sel_hi:[1,0]
	v_pk_mul_f32 v[10:11], v[110:111], v[2:3] op_sel_hi:[1,0]
	v_pk_fma_f32 v[8:9], v[44:45], v[8:9], v[28:29]
	v_pk_fma_f32 v[10:11], v[46:47], v[10:11], v[30:31]
	v_cvt_pk_bf16_f32 v60, v8, v9
	v_cvt_pk_bf16_f32 v61, v10, v11
	global_store_dwordx2 v82, v[60:61], s[98:99] offset:1024
	v_pk_mul_f32 v[12:13], v[124:125], v[4:5] op_sel_hi:[1,0]
	v_pk_mul_f32 v[14:15], v[126:127], v[4:5] op_sel_hi:[1,0]
	v_pk_fma_f32 v[12:13], v[44:45], v[12:13], v[28:29]
	v_pk_fma_f32 v[14:15], v[46:47], v[14:15], v[30:31]
	v_cvt_pk_bf16_f32 v62, v12, v13
	v_cvt_pk_bf16_f32 v63, v14, v15
	global_store_dwordx2 v82, v[62:63], s[98:99] offset:3072
	v_pk_add_f32 v[48:49], v[48:49], 1.0 op_sel_hi:[1,0]
	v_pk_add_f32 v[50:51], v[50:51], 1.0 op_sel_hi:[1,0]
	v_pk_mul_f32 v[8:9], v[112:113], v[2:3] op_sel_hi:[1,0]
	v_pk_mul_f32 v[10:11], v[114:115], v[2:3] op_sel_hi:[1,0]
	v_pk_fma_f32 v[8:9], v[48:49], v[8:9], v[32:33]
	v_pk_fma_f32 v[10:11], v[50:51], v[10:11], v[34:35]
	v_cvt_pk_bf16_f32 v64, v8, v9
	v_cvt_pk_bf16_f32 v65, v10, v11
	global_store_dwordx2 v82, v[64:65], s[98:99] offset:1536
	v_pk_mul_f32 v[12:13], v[128:129], v[4:5] op_sel_hi:[1,0]
	v_pk_mul_f32 v[14:15], v[130:131], v[4:5] op_sel_hi:[1,0]
	v_pk_fma_f32 v[12:13], v[48:49], v[12:13], v[32:33]
	v_pk_fma_f32 v[14:15], v[50:51], v[14:15], v[34:35]
	v_cvt_pk_bf16_f32 v66, v12, v13
	v_cvt_pk_bf16_f32 v67, v14, v15
	global_store_dwordx2 v82, v[66:67], s[98:99] offset:3584
	s_mov_b32 s38, s100
	s_add_i32 s100, s38, s39
	s_cmp_lt_i32 s100, s68
	s_cbranch_scc0 .Lmd0_last_b
	s_min_i32 s0, s38, 0x4000
	s_ashr_i32 s0, s0, 13
	s_mul_i32 s0, s0, 0x6000
	s_add_u32 s56, s48, s0
	s_addc_u32 s57, s49, 0
	s_lshl_b32 s0, s38, 11
	s_add_u32 s98, s50, s0
	s_addc_u32 s99, s51, 0
	global_load_dwordx4 v[20:23], v80, s[56:57]
	global_load_dwordx4 v[24:27], v80, s[56:57] offset:1024
	global_load_dwordx4 v[28:31], v80, s[56:57] offset:2048
	global_load_dwordx4 v[32:35], v80, s[56:57] offset:3072
	global_load_dwordx4 v[36:39], v81, s[56:57]
	global_load_dwordx4 v[40:43], v81, s[56:57] offset:1024
	global_load_dwordx4 v[44:47], v81, s[56:57] offset:2048
	global_load_dwordx4 v[48:51], v81, s[56:57] offset:3072
	s_cmpk_lt_i32 s100, 0x4000
	s_cselect_b32 s0, s8, s34
	s_cselect_b32 s1, s9, s35
	s_cselect_b32 s56, 0, 0x4000
	s_sub_i32 s56, s100, s56
	s_lshl_b32 s56, s56, 12
	s_add_u32 s52, s0, s56
	s_addc_u32 s53, s1, 0
	global_load_dwordx4 v[100:103], v80, s[52:53]
	global_load_dwordx4 v[104:107], v80, s[52:53] offset:1024
	global_load_dwordx4 v[108:111], v80, s[52:53] offset:2048
	global_load_dwordx4 v[112:115], v80, s[52:53] offset:3072
	global_load_dwordx4 v[116:119], v81, s[52:53]
	global_load_dwordx4 v[120:123], v81, s[52:53] offset:1024
	global_load_dwordx4 v[124:127], v81, s[52:53] offset:2048
	global_load_dwordx4 v[128:131], v81, s[52:53] offset:3072
	s_waitcnt vmcnt(16)
	v_pk_mul_f32 v[8:9], v[132:133], v[132:133]
	v_pk_fma_f32 v[8:9], v[134:135], v[134:135], v[8:9]
	v_pk_fma_f32 v[8:9], v[136:137], v[136:137], v[8:9]
	v_pk_fma_f32 v[8:9], v[138:139], v[138:139], v[8:9]
	v_pk_fma_f32 v[8:9], v[140:141], v[140:141], v[8:9]
	v_pk_fma_f32 v[8:9], v[142:143], v[142:143], v[8:9]
	v_pk_fma_f32 v[8:9], v[144:145], v[144:145], v[8:9]
	v_pk_fma_f32 v[8:9], v[146:147], v[146:147], v[8:9]
	v_pk_mul_f32 v[10:11], v[148:149], v[148:149]
	v_pk_fma_f32 v[10:11], v[150:151], v[150:151], v[10:11]
	v_pk_fma_f32 v[10:11], v[152:153], v[152:153], v[10:11]
	v_pk_fma_f32 v[10:11], v[154:155], v[154:155], v[10:11]
	v_pk_fma_f32 v[10:11], v[156:157], v[156:157], v[10:11]
	v_pk_fma_f32 v[10:11], v[158:159], v[158:159], v[10:11]
	v_pk_fma_f32 v[10:11], v[160:161], v[160:161], v[10:11]
	v_pk_fma_f32 v[10:11], v[162:163], v[162:163], v[10:11]
	v_add_f32_e32 v6, v8, v9
	v_add_f32_e32 v7, v10, v11
	s_nop 1
	v_add_f32_dpp v6, v6, v6 quad_perm:[1,0,3,2] row_mask:0xf bank_mask:0xf
	v_add_f32_dpp v7, v7, v7 quad_perm:[1,0,3,2] row_mask:0xf bank_mask:0xf
	s_nop 1
	v_add_f32_dpp v6, v6, v6 quad_perm:[2,3,0,1] row_mask:0xf bank_mask:0xf
	v_add_f32_dpp v7, v7, v7 quad_perm:[2,3,0,1] row_mask:0xf bank_mask:0xf
	s_nop 1
	v_add_f32_dpp v6, v6, v6 row_half_mirror row_mask:0xf bank_mask:0xf
	v_add_f32_dpp v7, v7, v7 row_half_mirror row_mask:0xf bank_mask:0xf
	s_nop 1
	v_add_f32_dpp v6, v6, v6 row_mirror row_mask:0xf bank_mask:0xf
	v_add_f32_dpp v7, v7, v7 row_mirror row_mask:0xf bank_mask:0xf
	ds_bpermute_b32 v8, v83, v6
	ds_bpermute_b32 v9, v83, v7
	s_waitcnt lgkmcnt(0)
; template <bool COMBINE, bool MOD>
; __device__ __forceinline__ void phase_combine_modulate(const Params& p, int lprev, int lnext, const float* xlat, const float* xctx,
;                                                        float* olat, float* octx, int nrows) {
;     ...
;   for (int row0 = gw * R; row0 < nrows; row0 += nw * R) {
;     const bool lat = row0 < T_LAT;
;     const float* xr = lat ? xlat + (size_t)row0 * DM : xctx + (size_t)(row0 - T_LAT) * DM;
;     const int cond = row_cond(row0);
;     float4 v[R][4];
; #pragma unroll
;     for (int r = 0; r < R; ++r)
; #pragma unroll
;       for (int i = 0; i < 4; ++i) v[r][i] = *(const float4*)(xr + (size_t)r * DM + i * 256 + lane * 4);
;     ...
;     if (MOD) {
;       const float* sh = p.mada + (size_t)(lnext * 3 + cond) * 6144;
;       const float* sc = sh + 1024;
;       float rstd[R];
; #pragma unroll
;       for (int r = 0; r < R; ++r) {
;         float ss = 0.f;
; #pragma unroll
;         for (int i = 0; i < 4; ++i) ss += v[r][i].x * v[r][i].x + v[r][i].y * v[r][i].y + v[r][i].z * v[r][i].z + v[r][i].w * v[r][i].w;
;         rstd[r] = rsqrtf(wave_sum(ss) * (1.f / 1024.f) + 1e-6f);
;       }
; #pragma unroll
;       for (int i = 0; i < 4; ++i) {
;         const int col = i * 256 + lane * 4;
;         const float4 s4 = *(const float4*)(sc + col);
;         const float4 h4 = *(const float4*)(sh + col);
; #pragma unroll
;         for (int r = 0; r < R; ++r) {
;           u32x2 pk;
;           pk.x = pack2(v[r][i].x * rstd[r] * (1.f + s4.x) + h4.x, v[r][i].y * rstd[r] * (1.f + s4.y) + h4.y);
;           pk.y = pack2(v[r][i].z * rstd[r] * (1.f + s4.z) + h4.z, v[r][i].w * rstd[r] * (1.f + s4.w) + h4.w);
;           *(u32x2*)(p.H + (size_t)(row0 + r) * DM + col) = pk;
;         }
;       }
	v_pk_add_f32 v[6:7], v[6:7], v[8:9]
	ds_bpermute_b32 v8, v84, v6
	ds_bpermute_b32 v9, v84, v7
	s_waitcnt lgkmcnt(0)
	v_pk_add_f32 v[6:7], v[6:7], v[8:9]
	s_nop 0
	v_fma_f32 v6, v6, s101, v224
	v_fma_f32 v7, v7, s101, v224
	v_mul_f32_e32 v2, 0x4b800000, v6
	v_cmp_gt_f32_e32 vcc, s85, v6
	v_cndmask_b32_e32 v2, v6, v2, vcc
	v_rsq_f32_e32 v2, v2
	s_nop 0
	v_mul_f32_e32 v6, 0x45800000, v2
	v_cndmask_b32_e32 v2, v2, v6, vcc
	v_mul_f32_e32 v4, 0x4b800000, v7
	v_cmp_gt_f32_e32 vcc, s85, v7
	v_cndmask_b32_e32 v4, v7, v4, vcc
	v_rsq_f32_e32 v4, v4
	s_nop 0
	v_mul_f32_e32 v7, 0x45800000, v4
	v_cndmask_b32_e32 v4, v4, v7, vcc
	s_waitcnt vmcnt(8)
	v_pk_add_f32 v[36:37], v[36:37], 1.0 op_sel_hi:[1,0]
	v_pk_add_f32 v[38:39], v[38:39], 1.0 op_sel_hi:[1,0]
	v_pk_mul_f32 v[8:9], v[132:133], v[2:3] op_sel_hi:[1,0]
	v_pk_mul_f32 v[10:11], v[134:135], v[2:3] op_sel_hi:[1,0]
	v_pk_fma_f32 v[8:9], v[36:37], v[8:9], v[20:21]
	v_pk_fma_f32 v[10:11], v[38:39], v[10:11], v[22:23]
	v_cvt_pk_bf16_f32 v52, v8, v9
	v_cvt_pk_bf16_f32 v53, v10, v11
	global_store_dwordx2 v82, v[52:53], s[98:99]
	v_pk_mul_f32 v[12:13], v[148:149], v[4:5] op_sel_hi:[1,0]
	v_pk_mul_f32 v[14:15], v[150:151], v[4:5] op_sel_hi:[1,0]
	v_pk_fma_f32 v[12:13], v[36:37], v[12:13], v[20:21]
	v_pk_fma_f32 v[14:15], v[38:39], v[14:15], v[22:23]
	v_cvt_pk_bf16_f32 v54, v12, v13
	v_cvt_pk_bf16_f32 v55, v14, v15
	global_store_dwordx2 v82, v[54:55], s[98:99] offset:2048
	v_pk_add_f32 v[40:41], v[40:41], 1.0 op_sel_hi:[1,0]
	v_pk_add_f32 v[42:43], v[42:43], 1.0 op_sel_hi:[1,0]
	v_pk_mul_f32 v[8:9], v[136:137], v[2:3] op_sel_hi:[1,0]
	v_pk_mul_f32 v[10:11], v[138:139], v[2:3] op_sel_hi:[1,0]
	v_pk_fma_f32 v[8:9], v[40:41], v[8:9], v[24:25]
	v_pk_fma_f32 v[10:11], v[42:43], v[10:11], v[26:27]
	v_cvt_pk_bf16_f32 v56, v8, v9
	v_cvt_pk_bf16_f32 v57, v10, v11
	global_store_dwordx2 v82, v[56:57], s[98:99] offset:512
	v_pk_mul_f32 v[12:13], v[152:153], v[4:5] op_sel_hi:[1,0]
	v_pk_mul_f32 v[14:15], v[154:155], v[4:5] op_sel_hi:[1,0]
	v_pk_fma_f32 v[12:13], v[40:41], v[12:13], v[24:25]
	v_pk_fma_f32 v[14:15], v[42:43], v[14:15], v[26:27]
	v_cvt_pk_bf16_f32 v58, v12, v13
	v_cvt_pk_bf16_f32 v59, v14, v15
	global_store_dwordx2 v82, v[58:59], s[98:99] offset:2560
	v_pk_add_f32 v[44:45], v[44:45], 1.0 op_sel_hi:[1,0]
	v_pk_add_f32 v[46:47], v[46:47], 1.0 op_sel_hi:[1,0]
	v_pk_mul_f32 v[8:9], v[140:141], v[2:3] op_sel_hi:[1,0]
	v_pk_mul_f32 v[10:11], v[142:143], v[2:3] op_sel_hi:[1,0]
	v_pk_fma_f32 v[8:9], v[44:45], v[8:9], v[28:29]
	v_pk_fma_f32 v[10:11], v[46:47], v[10:11], v[30:31]
	v_cvt_pk_bf16_f32 v60, v8, v9
	v_cvt_pk_bf16_f32 v61, v10, v11
	global_store_dwordx2 v82, v[60:61], s[98:99] offset:1024
	v_pk_mul_f32 v[12:13], v[156:157], v[4:5] op_sel_hi:[1,0]
	v_pk_mul_f32 v[14:15], v[158:159], v[4:5] op_sel_hi:[1,0]
	v_pk_fma_f32 v[12:13], v[44:45], v[12:13], v[28:29]
	v_pk_fma_f32 v[14:15], v[46:47], v[14:15], v[30:31]
	v_cvt_pk_bf16_f32 v62, v12, v13
	v_cvt_pk_bf16_f32 v63, v14, v15
	global_store_dwordx2 v82, v[62:63], s[98:99] offset:3072
	v_pk_add_f32 v[48:49], v[48:49], 1.0 op_sel_hi:[1,0]
	v_pk_add_f32 v[50:51], v[50:51], 1.0 op_sel_hi:[1,0]
	v_pk_mul_f32 v[8:9], v[144:145], v[2:3] op_sel_hi:[1,0]
	v_pk_mul_f32 v[10:11], v[146:147], v[2:3] op_sel_hi:[1,0]
	v_pk_fma_f32 v[8:9], v[48:49], v[8:9], v[32:33]
	v_pk_fma_f32 v[10:11], v[50:51], v[10:11], v[34:35]
	v_cvt_pk_bf16_f32 v64, v8, v9
	v_cvt_pk_bf16_f32 v65, v10, v11
	global_store_dwordx2 v82, v[64:65], s[98:99] offset:1536
	v_pk_mul_f32 v[12:13], v[160:161], v[4:5] op_sel_hi:[1,0]
	v_pk_mul_f32 v[14:15], v[162:163], v[4:5] op_sel_hi:[1,0]
	v_pk_fma_f32 v[12:13], v[48:49], v[12:13], v[32:33]
	v_pk_fma_f32 v[14:15], v[50:51], v[14:15], v[34:35]
	v_cvt_pk_bf16_f32 v66, v12, v13
	v_cvt_pk_bf16_f32 v67, v14, v15
	global_store_dwordx2 v82, v[66:67], s[98:99] offset:3584
	s_mov_b32 s38, s100
	s_branch .Lmd0_loop
.Lmd0_last_a:
	s_min_i32 s0, s38, 0x4000
	s_ashr_i32 s0, s0, 13
	s_mul_i32 s0, s0, 0x6000
	s_add_u32 s56, s48, s0
	s_addc_u32 s57, s49, 0
	s_lshl_b32 s0, s38, 11
	s_add_u32 s98, s50, s0
	s_addc_u32 s99, s51, 0
	global_load_dwordx4 v[20:23], v80, s[56:57]
	global_load_dwordx4 v[24:27], v80, s[56:57] offset:1024
	global_load_dwordx4 v[28:31], v80, s[56:57] offset:2048
	global_load_dwordx4 v[32:35], v80, s[56:57] offset:3072
	global_load_dwordx4 v[36:39], v81, s[56:57]
	global_load_dwordx4 v[40:43], v81, s[56:57] offset:1024
	global_load_dwordx4 v[44:47], v81, s[56:57] offset:2048
	global_load_dwordx4 v[48:51], v81, s[56:57] offset:3072
	s_waitcnt vmcnt(8)
	v_pk_mul_f32 v[8:9], v[100:101], v[100:101]
	v_pk_fma_f32 v[8:9], v[102:103], v[102:103], v[8:9]
	v_pk_fma_f32 v[8:9], v[104:105], v[104:105], v[8:9]
	v_pk_fma_f32 v[8:9], v[106:107], v[106:107], v[8:9]
	v_pk_fma_f32 v[8:9], v[108:109], v[108:109], v[8:9]
	v_pk_fma_f32 v[8:9], v[110:111], v[110:111], v[8:9]
	v_pk_fma_f32 v[8:9], v[112:113], v[112:113], v[8:9]
	v_pk_fma_f32 v[8:9], v[114:115], v[114:115], v[8:9]
	v_pk_mul_f32 v[10:11], v[116:117], v[116:117]
	v_pk_fma_f32 v[10:11], v[118:119], v[118:119], v[10:11]
	v_pk_fma_f32 v[10:11], v[120:121], v[120:121], v[10:11]
	v_pk_fma_f32 v[10:11], v[122:123], v[122:123], v[10:11]
	v_pk_fma_f32 v[10:11], v[124:125], v[124:125], v[10:11]
	v_pk_fma_f32 v[10:11], v[126:127], v[126:127], v[10:11]
	v_pk_fma_f32 v[10:11], v[128:129], v[128:129], v[10:11]
	v_pk_fma_f32 v[10:11], v[130:131], v[130:131], v[10:11]
	v_add_f32_e32 v6, v8, v9
	v_add_f32_e32 v7, v10, v11
	s_nop 1
	v_add_f32_dpp v6, v6, v6 quad_perm:[1,0,3,2] row_mask:0xf bank_mask:0xf
	v_add_f32_dpp v7, v7, v7 quad_perm:[1,0,3,2] row_mask:0xf bank_mask:0xf
	s_nop 1
	v_add_f32_dpp v6, v6, v6 quad_perm:[2,3,0,1] row_mask:0xf bank_mask:0xf
	v_add_f32_dpp v7, v7, v7 quad_perm:[2,3,0,1] row_mask:0xf bank_mask:0xf
	s_nop 1
	v_add_f32_dpp v6, v6, v6 row_half_mirror row_mask:0xf bank_mask:0xf
	v_add_f32_dpp v7, v7, v7 row_half_mirror row_mask:0xf bank_mask:0xf
	s_nop 1
	v_add_f32_dpp v6, v6, v6 row_mirror row_mask:0xf bank_mask:0xf
	v_add_f32_dpp v7, v7, v7 row_mirror row_mask:0xf bank_mask:0xf
	ds_bpermute_b32 v8, v83, v6
	ds_bpermute_b32 v9, v83, v7
	s_waitcnt lgkmcnt(0)
; template <bool COMBINE, bool MOD>
; __device__ __forceinline__ void phase_combine_modulate(const Params& p, int lprev, int lnext, const float* xlat, const float* xctx,
;                                                        float* olat, float* octx, int nrows) {
;     ...
;         rstd[r] = rsqrtf(wave_sum(ss) * (1.f / 1024.f) + 1e-6f);
;       }
; #pragma unroll
;       for (int i = 0; i < 4; ++i) {
;         const int col = i * 256 + lane * 4;
;         const float4 s4 = *(const float4*)(sc + col);
;         const float4 h4 = *(const float4*)(sh + col);
; #pragma unroll
;         for (int r = 0; r < R; ++r) {
;           u32x2 pk;
;           pk.x = pack2(v[r][i].x * rstd[r] * (1.f + s4.x) + h4.x, v[r][i].y * rstd[r] * (1.f + s4.y) + h4.y);
;           pk.y = pack2(v[r][i].z * rstd[r] * (1.f + s4.z) + h4.z, v[r][i].w * rstd[r] * (1.f + s4.w) + h4.w);
;           *(u32x2*)(p.H + (size_t)(row0 + r) * DM + col) = pk;
;         }
;       }
	v_pk_add_f32 v[6:7], v[6:7], v[8:9]
	ds_bpermute_b32 v8, v84, v6
	ds_bpermute_b32 v9, v84, v7
	s_waitcnt lgkmcnt(0)
	v_pk_add_f32 v[6:7], v[6:7], v[8:9]
	s_nop 0
	v_fma_f32 v6, v6, s101, v224
	v_fma_f32 v7, v7, s101, v224
	v_mul_f32_e32 v2, 0x4b800000, v6
	v_cmp_gt_f32_e32 vcc, s85, v6
	v_cndmask_b32_e32 v2, v6, v2, vcc
	v_rsq_f32_e32 v2, v2
	s_nop 0
	v_mul_f32_e32 v6, 0x45800000, v2
	v_cndmask_b32_e32 v2, v2, v6, vcc
	v_mul_f32_e32 v4, 0x4b800000, v7
	v_cmp_gt_f32_e32 vcc, s85, v7
	v_cndmask_b32_e32 v4, v7, v4, vcc
	v_rsq_f32_e32 v4, v4
	s_nop 0
	v_mul_f32_e32 v7, 0x45800000, v4
	v_cndmask_b32_e32 v4, v4, v7, vcc
	s_waitcnt vmcnt(0)
	v_pk_add_f32 v[36:37], v[36:37], 1.0 op_sel_hi:[1,0]
	v_pk_add_f32 v[38:39], v[38:39], 1.0 op_sel_hi:[1,0]
	v_pk_mul_f32 v[8:9], v[100:101], v[2:3] op_sel_hi:[1,0]
	v_pk_mul_f32 v[10:11], v[102:103], v[2:3] op_sel_hi:[1,0]
	v_pk_fma_f32 v[8:9], v[36:37], v[8:9], v[20:21]
	v_pk_fma_f32 v[10:11], v[38:39], v[10:11], v[22:23]
	v_cvt_pk_bf16_f32 v52, v8, v9
	v_cvt_pk_bf16_f32 v53, v10, v11
	global_store_dwordx2 v82, v[52:53], s[98:99]
	v_pk_mul_f32 v[12:13], v[116:117], v[4:5] op_sel_hi:[1,0]
	v_pk_mul_f32 v[14:15], v[118:119], v[4:5] op_sel_hi:[1,0]
	v_pk_fma_f32 v[12:13], v[36:37], v[12:13], v[20:21]
	v_pk_fma_f32 v[14:15], v[38:39], v[14:15], v[22:23]
	v_cvt_pk_bf16_f32 v54, v12, v13
	v_cvt_pk_bf16_f32 v55, v14, v15
	global_store_dwordx2 v82, v[54:55], s[98:99] offset:2048
	v_pk_add_f32 v[40:41], v[40:41], 1.0 op_sel_hi:[1,0]
	v_pk_add_f32 v[42:43], v[42:43], 1.0 op_sel_hi:[1,0]
	v_pk_mul_f32 v[8:9], v[104:105], v[2:3] op_sel_hi:[1,0]
	v_pk_mul_f32 v[10:11], v[106:107], v[2:3] op_sel_hi:[1,0]
	v_pk_fma_f32 v[8:9], v[40:41], v[8:9], v[24:25]
	v_pk_fma_f32 v[10:11], v[42:43], v[10:11], v[26:27]
	v_cvt_pk_bf16_f32 v56, v8, v9
	v_cvt_pk_bf16_f32 v57, v10, v11
	global_store_dwordx2 v82, v[56:57], s[98:99] offset:512
	v_pk_mul_f32 v[12:13], v[120:121], v[4:5] op_sel_hi:[1,0]
	v_pk_mul_f32 v[14:15], v[122:123], v[4:5] op_sel_hi:[1,0]
	v_pk_fma_f32 v[12:13], v[40:41], v[12:13], v[24:25]
	v_pk_fma_f32 v[14:15], v[42:43], v[14:15], v[26:27]
	v_cvt_pk_bf16_f32 v58, v12, v13
	v_cvt_pk_bf16_f32 v59, v14, v15
	global_store_dwordx2 v82, v[58:59], s[98:99] offset:2560
	v_pk_add_f32 v[44:45], v[44:45], 1.0 op_sel_hi:[1,0]
	v_pk_add_f32 v[46:47], v[46:47], 1.0 op_sel_hi:[1,0]
	v_pk_mul_f32 v[8:9], v[108:109], v[2:3] op_sel_hi:[1,0]
	v_pk_mul_f32 v[10:11], v[110:111], v[2:3] op_sel_hi:[1,0]
	v_pk_fma_f32 v[8:9], v[44:45], v[8:9], v[28:29]
	v_pk_fma_f32 v[10:11], v[46:47], v[10:11], v[30:31]
	v_cvt_pk_bf16_f32 v60, v8, v9
	v_cvt_pk_bf16_f32 v61, v10, v11
	global_store_dwordx2 v82, v[60:61], s[98:99] offset:1024
	v_pk_mul_f32 v[12:13], v[124:125], v[4:5] op_sel_hi:[1,0]
	v_pk_mul_f32 v[14:15], v[126:127], v[4:5] op_sel_hi:[1,0]
	v_pk_fma_f32 v[12:13], v[44:45], v[12:13], v[28:29]
	v_pk_fma_f32 v[14:15], v[46:47], v[14:15], v[30:31]
	v_cvt_pk_bf16_f32 v62, v12, v13
	v_cvt_pk_bf16_f32 v63, v14, v15
	global_store_dwordx2 v82, v[62:63], s[98:99] offset:3072
	v_pk_add_f32 v[48:49], v[48:49], 1.0 op_sel_hi:[1,0]
	v_pk_add_f32 v[50:51], v[50:51], 1.0 op_sel_hi:[1,0]
	v_pk_mul_f32 v[8:9], v[112:113], v[2:3] op_sel_hi:[1,0]
	v_pk_mul_f32 v[10:11], v[114:115], v[2:3] op_sel_hi:[1,0]
	v_pk_fma_f32 v[8:9], v[48:49], v[8:9], v[32:33]
	v_pk_fma_f32 v[10:11], v[50:51], v[10:11], v[34:35]
	v_cvt_pk_bf16_f32 v64, v8, v9
	v_cvt_pk_bf16_f32 v65, v10, v11
	global_store_dwordx2 v82, v[64:65], s[98:99] offset:1536
	v_pk_mul_f32 v[12:13], v[128:129], v[4:5] op_sel_hi:[1,0]
	v_pk_mul_f32 v[14:15], v[130:131], v[4:5] op_sel_hi:[1,0]
	v_pk_fma_f32 v[12:13], v[48:49], v[12:13], v[32:33]
	v_pk_fma_f32 v[14:15], v[50:51], v[14:15], v[34:35]
	v_cvt_pk_bf16_f32 v66, v12, v13
	v_cvt_pk_bf16_f32 v67, v14, v15
	global_store_dwordx2 v82, v[66:67], s[98:99] offset:3584
	s_branch .Lmd0_done
; template <bool COMBINE, bool MOD>
; __device__ __forceinline__ void phase_combine_modulate(const Params& p, int lprev, int lnext, const float* xlat, const float* xctx,
;                                                        float* olat, float* octx, int nrows) {
;     ...
;     if (MOD) {
;       const float* sh = p.mada + (size_t)(lnext * 3 + cond) * 6144;
;       const float* sc = sh + 1024;
;       float rstd[R];
; #pragma unroll
;       for (int r = 0; r < R; ++r) {
;         float ss = 0.f;
; #pragma unroll
;         for (int i = 0; i < 4; ++i) ss += v[r][i].x * v[r][i].x + v[r][i].y * v[r][i].y + v[r][i].z * v[r][i].z + v[r][i].w * v[r][i].w;
;         rstd[r] = rsqrtf(wave_sum(ss) * (1.f / 1024.f) + 1e-6f);
;       }
; #pragma unroll
;       for (int i = 0; i < 4; ++i) {
;         const int col = i * 256 + lane * 4;
;         const float4 s4 = *(const float4*)(sc + col);
;         const float4 h4 = *(const float4*)(sh + col);
; #pragma unroll
;         for (int r = 0; r < R; ++r) {
;           u32x2 pk;
;           pk.x = pack2(v[r][i].x * rstd[r] * (1.f + s4.x) + h4.x, v[r][i].y * rstd[r] * (1.f + s4.y) + h4.y);
;           pk.y = pack2(v[r][i].z * rstd[r] * (1.f + s4.z) + h4.z, v[r][i].w * rstd[r] * (1.f + s4.w) + h4.w);
;           *(u32x2*)(p.H + (size_t)(row0 + r) * DM + col) = pk;
;         }
;       }
.Lmd0_last_b:
	s_min_i32 s0, s38, 0x4000
	s_ashr_i32 s0, s0, 13
	s_mul_i32 s0, s0, 0x6000
	s_add_u32 s56, s48, s0
	s_addc_u32 s57, s49, 0
	s_lshl_b32 s0, s38, 11
	s_add_u32 s98, s50, s0
	s_addc_u32 s99, s51, 0
	global_load_dwordx4 v[20:23], v80, s[56:57]
	global_load_dwordx4 v[24:27], v80, s[56:57] offset:1024
	global_load_dwordx4 v[28:31], v80, s[56:57] offset:2048
	global_load_dwordx4 v[32:35], v80, s[56:57] offset:3072
	global_load_dwordx4 v[36:39], v81, s[56:57]
	global_load_dwordx4 v[40:43], v81, s[56:57] offset:1024
	global_load_dwordx4 v[44:47], v81, s[56:57] offset:2048
	global_load_dwordx4 v[48:51], v81, s[56:57] offset:3072
	s_waitcnt vmcnt(8)
	v_pk_mul_f32 v[8:9], v[132:133], v[132:133]
	v_pk_fma_f32 v[8:9], v[134:135], v[134:135], v[8:9]
	v_pk_fma_f32 v[8:9], v[136:137], v[136:137], v[8:9]
	v_pk_fma_f32 v[8:9], v[138:139], v[138:139], v[8:9]
	v_pk_fma_f32 v[8:9], v[140:141], v[140:141], v[8:9]
	v_pk_fma_f32 v[8:9], v[142:143], v[142:143], v[8:9]
	v_pk_fma_f32 v[8:9], v[144:145], v[144:145], v[8:9]
	v_pk_fma_f32 v[8:9], v[146:147], v[146:147], v[8:9]
	v_pk_mul_f32 v[10:11], v[148:149], v[148:149]
	v_pk_fma_f32 v[10:11], v[150:151], v[150:151], v[10:11]
	v_pk_fma_f32 v[10:11], v[152:153], v[152:153], v[10:11]
	v_pk_fma_f32 v[10:11], v[154:155], v[154:155], v[10:11]
	v_pk_fma_f32 v[10:11], v[156:157], v[156:157], v[10:11]
	v_pk_fma_f32 v[10:11], v[158:159], v[158:159], v[10:11]
	v_pk_fma_f32 v[10:11], v[160:161], v[160:161], v[10:11]
	v_pk_fma_f32 v[10:11], v[162:163], v[162:163], v[10:11]
	v_add_f32_e32 v6, v8, v9
	v_add_f32_e32 v7, v10, v11
	s_nop 1
	v_add_f32_dpp v6, v6, v6 quad_perm:[1,0,3,2] row_mask:0xf bank_mask:0xf
	v_add_f32_dpp v7, v7, v7 quad_perm:[1,0,3,2] row_mask:0xf bank_mask:0xf
	s_nop 1
	v_add_f32_dpp v6, v6, v6 quad_perm:[2,3,0,1] row_mask:0xf bank_mask:0xf
	v_add_f32_dpp v7, v7, v7 quad_perm:[2,3,0,1] row_mask:0xf bank_mask:0xf
	s_nop 1
	v_add_f32_dpp v6, v6, v6 row_half_mirror row_mask:0xf bank_mask:0xf
	v_add_f32_dpp v7, v7, v7 row_half_mirror row_mask:0xf bank_mask:0xf
	s_nop 1
	v_add_f32_dpp v6, v6, v6 row_mirror row_mask:0xf bank_mask:0xf
	v_add_f32_dpp v7, v7, v7 row_mirror row_mask:0xf bank_mask:0xf
	ds_bpermute_b32 v8, v83, v6
	ds_bpermute_b32 v9, v83, v7
	s_waitcnt lgkmcnt(0)
	v_pk_add_f32 v[6:7], v[6:7], v[8:9]
	ds_bpermute_b32 v8, v84, v6
	ds_bpermute_b32 v9, v84, v7
	s_waitcnt lgkmcnt(0)
	v_pk_add_f32 v[6:7], v[6:7], v[8:9]
	s_nop 0
	v_fma_f32 v6, v6, s101, v224
	v_fma_f32 v7, v7, s101, v224
	v_mul_f32_e32 v2, 0x4b800000, v6
	v_cmp_gt_f32_e32 vcc, s85, v6
	v_cndmask_b32_e32 v2, v6, v2, vcc
	v_rsq_f32_e32 v2, v2
	s_nop 0
	v_mul_f32_e32 v6, 0x45800000, v2
	v_cndmask_b32_e32 v2, v2, v6, vcc
	v_mul_f32_e32 v4, 0x4b800000, v7
	v_cmp_gt_f32_e32 vcc, s85, v7
	v_cndmask_b32_e32 v4, v7, v4, vcc
	v_rsq_f32_e32 v4, v4
	s_nop 0
	v_mul_f32_e32 v7, 0x45800000, v4
	v_cndmask_b32_e32 v4, v4, v7, vcc
	s_waitcnt vmcnt(0)
	v_pk_add_f32 v[36:37], v[36:37], 1.0 op_sel_hi:[1,0]
	v_pk_add_f32 v[38:39], v[38:39], 1.0 op_sel_hi:[1,0]
	v_pk_mul_f32 v[8:9], v[132:133], v[2:3] op_sel_hi:[1,0]
	v_pk_mul_f32 v[10:11], v[134:135], v[2:3] op_sel_hi:[1,0]
	v_pk_fma_f32 v[8:9], v[36:37], v[8:9], v[20:21]
	v_pk_fma_f32 v[10:11], v[38:39], v[10:11], v[22:23]
	v_cvt_pk_bf16_f32 v52, v8, v9
	v_cvt_pk_bf16_f32 v53, v10, v11
	global_store_dwordx2 v82, v[52:53], s[98:99]
	v_pk_mul_f32 v[12:13], v[148:149], v[4:5] op_sel_hi:[1,0]
	v_pk_mul_f32 v[14:15], v[150:151], v[4:5] op_sel_hi:[1,0]
	v_pk_fma_f32 v[12:13], v[36:37], v[12:13], v[20:21]
	v_pk_fma_f32 v[14:15], v[38:39], v[14:15], v[22:23]
	v_cvt_pk_bf16_f32 v54, v12, v13
	v_cvt_pk_bf16_f32 v55, v14, v15
	global_store_dwordx2 v82, v[54:55], s[98:99] offset:2048
	v_pk_add_f32 v[40:41], v[40:41], 1.0 op_sel_hi:[1,0]
	v_pk_add_f32 v[42:43], v[42:43], 1.0 op_sel_hi:[1,0]
	v_pk_mul_f32 v[8:9], v[136:137], v[2:3] op_sel_hi:[1,0]
	v_pk_mul_f32 v[10:11], v[138:139], v[2:3] op_sel_hi:[1,0]
	v_pk_fma_f32 v[8:9], v[40:41], v[8:9], v[24:25]
	v_pk_fma_f32 v[10:11], v[42:43], v[10:11], v[26:27]
	v_cvt_pk_bf16_f32 v56, v8, v9
	v_cvt_pk_bf16_f32 v57, v10, v11
	global_store_dwordx2 v82, v[56:57], s[98:99] offset:512
	v_pk_mul_f32 v[12:13], v[152:153], v[4:5] op_sel_hi:[1,0]
	v_pk_mul_f32 v[14:15], v[154:155], v[4:5] op_sel_hi:[1,0]
	v_pk_fma_f32 v[12:13], v[40:41], v[12:13], v[24:25]
	v_pk_fma_f32 v[14:15], v[42:43], v[14:15], v[26:27]
	v_cvt_pk_bf16_f32 v58, v12, v13
	v_cvt_pk_bf16_f32 v59, v14, v15
	global_store_dwordx2 v82, v[58:59], s[98:99] offset:2560
	v_pk_add_f32 v[44:45], v[44:45], 1.0 op_sel_hi:[1,0]
	v_pk_add_f32 v[46:47], v[46:47], 1.0 op_sel_hi:[1,0]
	v_pk_mul_f32 v[8:9], v[140:141], v[2:3] op_sel_hi:[1,0]
	v_pk_mul_f32 v[10:11], v[142:143], v[2:3] op_sel_hi:[1,0]
	v_pk_fma_f32 v[8:9], v[44:45], v[8:9], v[28:29]
	v_pk_fma_f32 v[10:11], v[46:47], v[10:11], v[30:31]
	v_cvt_pk_bf16_f32 v60, v8, v9
	v_cvt_pk_bf16_f32 v61, v10, v11
	global_store_dwordx2 v82, v[60:61], s[98:99] offset:1024
	v_pk_mul_f32 v[12:13], v[156:157], v[4:5] op_sel_hi:[1,0]
	v_pk_mul_f32 v[14:15], v[158:159], v[4:5] op_sel_hi:[1,0]
	v_pk_fma_f32 v[12:13], v[44:45], v[12:13], v[28:29]
	v_pk_fma_f32 v[14:15], v[46:47], v[14:15], v[30:31]
	v_cvt_pk_bf16_f32 v62, v12, v13
	v_cvt_pk_bf16_f32 v63, v14, v15
	global_store_dwordx2 v82, v[62:63], s[98:99] offset:3072
	v_pk_add_f32 v[48:49], v[48:49], 1.0 op_sel_hi:[1,0]
	v_pk_add_f32 v[50:51], v[50:51], 1.0 op_sel_hi:[1,0]
	v_pk_mul_f32 v[8:9], v[144:145], v[2:3] op_sel_hi:[1,0]
	v_pk_mul_f32 v[10:11], v[146:147], v[2:3] op_sel_hi:[1,0]
	v_pk_fma_f32 v[8:9], v[48:49], v[8:9], v[32:33]
	v_pk_fma_f32 v[10:11], v[50:51], v[10:11], v[34:35]
	v_cvt_pk_bf16_f32 v64, v8, v9
	v_cvt_pk_bf16_f32 v65, v10, v11
	global_store_dwordx2 v82, v[64:65], s[98:99] offset:1536
	v_pk_mul_f32 v[12:13], v[160:161], v[4:5] op_sel_hi:[1,0]
	v_pk_mul_f32 v[14:15], v[162:163], v[4:5] op_sel_hi:[1,0]
	v_pk_fma_f32 v[12:13], v[48:49], v[12:13], v[32:33]
	v_pk_fma_f32 v[14:15], v[50:51], v[14:15], v[34:35]
	v_cvt_pk_bf16_f32 v66, v12, v13
	v_cvt_pk_bf16_f32 v67, v14, v15
	global_store_dwordx2 v82, v[66:67], s[98:99] offset:3584
.Lmd0_done:
.LBB0_155:
	s_or_b64 exec, exec, s[40:41]
	s_mov_b64 s[0:1], 0
